# grid barrier: the XCD leader releases its XCD (XGEN atomic) before its own buffer_inv instead of after; same acquire/release semantics for the waiting workgroups
# baseline (speedup 1.0000x reference)
; __device__ __forceinline__ unsigned xb_ld(unsigned* p)              { return __hip_atomic_load(p, __ATOMIC_RELAXED, __HIP_MEMORY_SCOPE_AGENT); }
; __device__ __forceinline__ unsigned xb_add(unsigned* p, unsigned v) { return __hip_atomic_fetch_add(p, v, __ATOMIC_RELAXED, __HIP_MEMORY_SCOPE_AGENT); }
; #define XB_SPIN(cond, bar) do { unsigned _sp = 0; while (cond) { __builtin_amdgcn_s_sleep(1); \
;     if ((++_sp & 255u) == 0u) { if (xb_ld(&(bar)[XB_TMO])) break; if (_sp > XB_SPIN_CAP) { atomicAdd(&(bar)[XB_TMO], 1u); break; } } } } while (0)
; __device__ __forceinline__ void xcd_barrier(const XcdBarrier& b) {
;     ...
;         if (old + 1u == (gen + 1u) * nloc) {
;             __builtin_amdgcn_fence(__ATOMIC_RELEASE, "agent");
;             asm volatile("s_waitcnt vmcnt(0)" ::: "memory");
;             const unsigned og = xb_add(&bar[XB_TOP], 1u);
;             const unsigned tg = og / nx;
;             if (og + 1u == (tg + 1u) * nx) xb_add(&bar[XB_TOPGEN], 1u);
;             else XB_SPIN(xb_ld(&bar[XB_TOPGEN]) == tg, bar);
;             __builtin_amdgcn_fence(__ATOMIC_ACQUIRE, "agent");
;             xb_add(&bar[XB_XGEN(b.x)], 1u);
;             asm volatile("s_waitcnt vmcnt(0)" ::: "memory");
.LBB0_108:
	s_or_b64 exec, exec, s[12:13]
	s_waitcnt vmcnt(0)
	global_atomic_add v[164:165], v244, off
	buffer_inv sc1
	s_waitcnt vmcnt(0)
